# fp8 K-loops: the eight MFMAs of each MMA call re-ordered n-major (B fragment operand fixed over four MFMAs), dependence-checked, hazard pads raised; order only
# speedup vs baseline: 1.0148x; 1.0010x over previous
.LBB0_1768:
	ds_read_b128 v[134:137], v157
	ds_read_b128 v[138:141], v157 offset:1024
	ds_read_b128 v[142:145], v157 offset:2048
	ds_read_b128 v[146:149], v157 offset:3072
	ds_read_b128 v[164:167], v158
	ds_read_b128 v[168:171], v158 offset:1024
	ds_read_b128 v[172:175], v158 offset:2048
	ds_read_b128 v[176:179], v158 offset:3072
	s_add_u32 s2, s56, 0x10000
	s_addc_u32 s3, s57, 0
	s_cmp_eq_u32 s96, 28
	s_cselect_b32 s58, s43, s2
	s_cselect_b32 s59, s5, s3
	s_cselect_b32 s64, s49, s92
	s_cselect_b32 s65, s41, s93
	s_add_u32 s60, s58, 0x8000
	s_addc_u32 s61, s59, 0
	ds_read_b128 v[180:183], v159
	ds_read_b128 v[184:187], v159 offset:1024
	ds_read_b128 v[188:191], v159 offset:2048
	ds_read_b128 v[192:195], v159 offset:3072
	ds_read_b128 v[196:199], v159 offset:4096
	ds_read_b128 v[200:203], v159 offset:5120
	ds_read_b128 v[204:207], v159 offset:6144
	ds_read_b128 v[208:211], v159 offset:7168
	s_add_u32 s8, s56, 0xc000
	s_addc_u32 s9, s57, 0
	s_mov_b32 m0, s75
	s_nop 0
	global_load_lds_dwordx4 v156, s[8:9]
	s_add_u32 s8, s56, 0xe000
	s_addc_u32 s9, s57, 0
	s_mov_b32 m0, s81
	s_nop 0
	global_load_lds_dwordx4 v156, s[8:9]
	s_waitcnt vmcnt(8)
	s_waitcnt lgkmcnt(0)
	s_barrier
	s_setprio 1
	s_waitcnt lgkmcnt(6)
	s_waitcnt lgkmcnt(0)
	v_mfma_scale_f32_16x16x128_f8f6f4 v[124:127], v[134:141], v[180:187], v[124:127], v160, v160 op_sel_hi:[0,0,0]
	v_mfma_scale_f32_16x16x128_f8f6f4 v[108:111], v[134:141], v[188:195], v[108:111], v160, v160 op_sel_hi:[0,0,0]
	v_mfma_scale_f32_16x16x128_f8f6f4 v[150:153], v[134:141], v[196:203], v[92:95], v160, v160 op_sel_hi:[0,0,0]
	v_mfma_scale_f32_16x16x128_f8f6f4 v[216:219], v[134:141], v[204:211], v[76:79], v160, v160 op_sel_hi:[0,0,0]
	v_mfma_scale_f32_16x16x128_f8f6f4 v[220:223], v[142:149], v[204:211], v[68:71], v160, v160 op_sel_hi:[0,0,0]
	v_mfma_scale_f32_16x16x128_f8f6f4 v[212:215], v[142:149], v[196:203], v[84:87], v160, v160 op_sel_hi:[0,0,0]
	v_mfma_scale_f32_16x16x128_f8f6f4 v[100:103], v[142:149], v[188:195], v[100:103], v160, v160 op_sel_hi:[0,0,0]
	v_mfma_scale_f32_16x16x128_f8f6f4 v[116:119], v[142:149], v[180:187], v[116:119], v160, v160 op_sel_hi:[0,0,0]
	s_setprio 0
	s_setprio 1
	v_mfma_scale_f32_16x16x128_f8f6f4 v[120:123], v[164:171], v[180:187], v[120:123], v160, v160 op_sel_hi:[0,0,0]
	v_mfma_scale_f32_16x16x128_f8f6f4 v[112:115], v[172:179], v[180:187], v[112:115], v160, v160 op_sel_hi:[0,0,0]
	v_mfma_scale_f32_16x16x128_f8f6f4 v[104:107], v[164:171], v[188:195], v[104:107], v160, v160 op_sel_hi:[0,0,0]
	v_mfma_scale_f32_16x16x128_f8f6f4 v[96:99], v[172:179], v[188:195], v[96:99], v160, v160 op_sel_hi:[0,0,0]
	v_mfma_scale_f32_16x16x128_f8f6f4 v[180:183], v[164:171], v[196:203], v[88:91], v160, v160 op_sel_hi:[0,0,0]
	v_mfma_scale_f32_16x16x128_f8f6f4 v[184:187], v[172:179], v[196:203], v[80:83], v160, v160 op_sel_hi:[0,0,0]
	v_mfma_scale_f32_16x16x128_f8f6f4 v[188:191], v[164:171], v[204:211], v[72:75], v160, v160 op_sel_hi:[0,0,0]
	v_mfma_scale_f32_16x16x128_f8f6f4 v[192:195], v[172:179], v[204:211], v[64:67], v160, v160 op_sel_hi:[0,0,0]
	s_setprio 0
	s_barrier
	s_nop 11
	s_add_u32 s8, s64, 0x2000
	s_nop 3
	ds_read_b128 v[64:67], v159 offset:16384
	ds_read_b128 v[68:71], v159 offset:17408
	ds_read_b128 v[72:75], v159 offset:18432
	ds_read_b128 v[76:79], v159 offset:19456
	ds_read_b128 v[80:83], v159 offset:20480
	ds_read_b128 v[84:87], v159 offset:21504
	ds_read_b128 v[88:91], v159 offset:22528
	ds_read_b128 v[92:95], v159 offset:23552
	s_mov_b32 m0, s54
	s_nop 0
	global_load_lds_dwordx4 v156, s[64:65]
	s_addc_u32 s9, s65, 0
	s_mov_b32 m0, s55
	s_nop 0
	global_load_lds_dwordx4 v156, s[8:9]
	s_add_u32 s8, s64, 0x4000
	s_addc_u32 s9, s65, 0
	s_mov_b32 m0, s62
	s_nop 0
	global_load_lds_dwordx4 v156, s[8:9]
	s_add_u32 s8, s64, 0x6000
	s_addc_u32 s9, s65, 0
	s_mov_b32 m0, s63
	s_nop 0
	global_load_lds_dwordx4 v156, s[8:9]
	s_add_u32 s8, s58, 0x2000
	s_mov_b32 m0, s53
	s_nop 0
	global_load_lds_dwordx4 v156, s[58:59]
	s_addc_u32 s9, s59, 0
	s_mov_b32 m0, s66
	s_nop 0
	global_load_lds_dwordx4 v156, s[8:9]
	s_waitcnt vmcnt(8)
	s_waitcnt lgkmcnt(0)
	s_barrier
	s_setprio 1
	s_waitcnt lgkmcnt(6)
	s_waitcnt lgkmcnt(0)
	v_mfma_scale_f32_16x16x128_f8f6f4 v[56:59], v[134:141], v[64:71], v[56:59], v160, v160 op_sel_hi:[0,0,0]
	v_mfma_scale_f32_16x16x128_f8f6f4 v[44:47], v[134:141], v[72:79], v[44:47], v160, v160 op_sel_hi:[0,0,0]
	v_mfma_scale_f32_16x16x128_f8f6f4 v[208:211], v[134:141], v[80:87], v[28:31], v160, v160 op_sel_hi:[0,0,0]
	v_mfma_scale_f32_16x16x128_f8f6f4 v[228:231], v[134:141], v[88:95], v[12:15], v160, v160 op_sel_hi:[0,0,0]
	v_mfma_scale_f32_16x16x128_f8f6f4 v[232:235], v[142:149], v[88:95], v[4:7], v160, v160 op_sel_hi:[0,0,0]
	v_mfma_scale_f32_16x16x128_f8f6f4 v[224:227], v[142:149], v[80:87], v[20:23], v160, v160 op_sel_hi:[0,0,0]
	v_mfma_scale_f32_16x16x128_f8f6f4 v[204:207], v[142:149], v[72:79], v[36:39], v160, v160 op_sel_hi:[0,0,0]
	v_mfma_scale_f32_16x16x128_f8f6f4 v[48:51], v[142:149], v[64:71], v[48:51], v160, v160 op_sel_hi:[0,0,0]
	s_setprio 0
	s_setprio 1
	s_waitcnt lgkmcnt(0)
	v_mfma_scale_f32_16x16x128_f8f6f4 v[60:63], v[164:171], v[64:71], v[60:63], v160, v160 op_sel_hi:[0,0,0]
	v_mfma_scale_f32_16x16x128_f8f6f4 v[40:43], v[164:171], v[72:79], v[40:43], v160, v160 op_sel_hi:[0,0,0]
	v_mfma_scale_f32_16x16x128_f8f6f4 v[240:243], v[164:171], v[80:87], v[24:27], v160, v160 op_sel_hi:[0,0,0]
	v_mfma_scale_f32_16x16x128_f8f6f4 v[248:251], v[164:171], v[88:95], v[8:11], v160, v160 op_sel_hi:[0,0,0]
	v_mfma_scale_f32_16x16x128_f8f6f4 v[128:131], v[172:179], v[88:95], v[0:3], v160, v160 op_sel_hi:[0,0,0]
	v_mfma_scale_f32_16x16x128_f8f6f4 v[244:247], v[172:179], v[80:87], v[16:19], v160, v160 op_sel_hi:[0,0,0]
	v_mfma_scale_f32_16x16x128_f8f6f4 v[236:239], v[172:179], v[72:79], v[32:35], v160, v160 op_sel_hi:[0,0,0]
	v_mfma_scale_f32_16x16x128_f8f6f4 v[52:55], v[172:179], v[64:71], v[52:55], v160, v160 op_sel_hi:[0,0,0]
	s_setprio 0
	s_barrier
	s_nop 11
	s_nop 4
	ds_read_b128 v[0:3], v161
	ds_read_b128 v[4:7], v161 offset:1024
	ds_read_b128 v[134:137], v161 offset:2048
	ds_read_b128 v[138:141], v161 offset:3072
	ds_read_b128 v[142:145], v162
	ds_read_b128 v[146:149], v162 offset:1024
	ds_read_b128 v[164:167], v162 offset:2048
	ds_read_b128 v[168:171], v162 offset:3072
	ds_read_b128 v[8:11], v159 offset:32768
	ds_read_b128 v[12:15], v159 offset:33792
	ds_read_b128 v[16:19], v159 offset:34816
	ds_read_b128 v[20:23], v159 offset:35840
	ds_read_b128 v[24:27], v159 offset:36864
	ds_read_b128 v[28:31], v159 offset:37888
	ds_read_b128 v[32:35], v159 offset:38912
	ds_read_b128 v[36:39], v159 offset:39936
	s_add_u32 s8, s58, 0x4000
	s_addc_u32 s9, s59, 0
	s_mov_b32 m0, s67
	s_nop 0
	global_load_lds_dwordx4 v156, s[8:9]
	s_add_u32 s8, s58, 0x6000
	s_addc_u32 s9, s59, 0
	s_mov_b32 m0, s68
	s_nop 0
	global_load_lds_dwordx4 v156, s[8:9]
	s_waitcnt vmcnt(8)
	s_waitcnt lgkmcnt(0)
	s_barrier
	s_setprio 1
	s_waitcnt lgkmcnt(6)
	s_waitcnt lgkmcnt(0)
	v_mfma_scale_f32_16x16x128_f8f6f4 v[124:127], v[0:7], v[8:15], v[124:127], v160, v160 op_sel_hi:[0,0,0]
	v_mfma_scale_f32_16x16x128_f8f6f4 v[108:111], v[0:7], v[16:23], v[108:111], v160, v160 op_sel_hi:[0,0,0]
	v_mfma_scale_f32_16x16x128_f8f6f4 v[92:95], v[0:7], v[24:31], v[150:153], v160, v160 op_sel_hi:[0,0,0]
	v_mfma_scale_f32_16x16x128_f8f6f4 v[76:79], v[0:7], v[32:39], v[216:219], v160, v160 op_sel_hi:[0,0,0]
	v_mfma_scale_f32_16x16x128_f8f6f4 v[68:71], v[134:141], v[32:39], v[220:223], v160, v160 op_sel_hi:[0,0,0]
	v_mfma_scale_f32_16x16x128_f8f6f4 v[84:87], v[134:141], v[24:31], v[212:215], v160, v160 op_sel_hi:[0,0,0]
	v_mfma_scale_f32_16x16x128_f8f6f4 v[100:103], v[134:141], v[16:23], v[100:103], v160, v160 op_sel_hi:[0,0,0]
	v_mfma_scale_f32_16x16x128_f8f6f4 v[116:119], v[134:141], v[8:15], v[116:119], v160, v160 op_sel_hi:[0,0,0]
	s_setprio 0
	s_setprio 1
	s_waitcnt lgkmcnt(0)
	v_mfma_scale_f32_16x16x128_f8f6f4 v[120:123], v[142:149], v[8:15], v[120:123], v160, v160 op_sel_hi:[0,0,0]
	v_mfma_scale_f32_16x16x128_f8f6f4 v[104:107], v[142:149], v[16:23], v[104:107], v160, v160 op_sel_hi:[0,0,0]
	v_mfma_scale_f32_16x16x128_f8f6f4 v[88:91], v[142:149], v[24:31], v[180:183], v160, v160 op_sel_hi:[0,0,0]
	v_mfma_scale_f32_16x16x128_f8f6f4 v[72:75], v[142:149], v[32:39], v[188:191], v160, v160 op_sel_hi:[0,0,0]
	v_mfma_scale_f32_16x16x128_f8f6f4 v[64:67], v[164:171], v[32:39], v[192:195], v160, v160 op_sel_hi:[0,0,0]
	v_mfma_scale_f32_16x16x128_f8f6f4 v[80:83], v[164:171], v[24:31], v[184:187], v160, v160 op_sel_hi:[0,0,0]
	v_mfma_scale_f32_16x16x128_f8f6f4 v[96:99], v[164:171], v[16:23], v[96:99], v160, v160 op_sel_hi:[0,0,0]
	v_mfma_scale_f32_16x16x128_f8f6f4 v[112:115], v[164:171], v[8:15], v[112:115], v160, v160 op_sel_hi:[0,0,0]
	s_setprio 0
	s_barrier
	s_nop 11
	s_add_u32 s8, s64, 0x8000
	s_addc_u32 s9, s65, 0
	ds_read_b128 v[172:175], v159 offset:49152
	ds_read_b128 v[176:179], v159 offset:50176
	ds_read_b128 v[180:183], v159 offset:51200
	ds_read_b128 v[184:187], v159 offset:52224
	ds_read_b128 v[188:191], v159 offset:53248
	ds_read_b128 v[192:195], v159 offset:54272
	ds_read_b128 v[196:199], v159 offset:55296
	ds_read_b128 v[200:203], v159 offset:56320
	s_mov_b32 m0, s69
	s_nop 0
	global_load_lds_dwordx4 v156, s[8:9]
	s_add_u32 s8, s64, 0xa000
	s_addc_u32 s9, s65, 0
	s_mov_b32 m0, s70
	s_nop 0
	global_load_lds_dwordx4 v156, s[8:9]
	s_add_u32 s8, s64, 0xc000
	s_addc_u32 s9, s65, 0
	s_mov_b32 m0, s73
	s_nop 0
	global_load_lds_dwordx4 v156, s[8:9]
	s_add_u32 s8, s64, 0xe000
	s_addc_u32 s9, s65, 0
	s_mov_b32 m0, s74
	s_nop 0
	global_load_lds_dwordx4 v156, s[8:9]
	s_add_u32 s8, s58, 0xa000
	s_mov_b32 m0, s71
	s_nop 0
	global_load_lds_dwordx4 v156, s[60:61]
	s_addc_u32 s9, s59, 0
	s_mov_b32 m0, s72
	s_nop 0
	global_load_lds_dwordx4 v156, s[8:9]
	s_waitcnt vmcnt(8)
	s_waitcnt lgkmcnt(0)
	s_barrier
	s_setprio 1
	s_waitcnt lgkmcnt(6)
	s_waitcnt lgkmcnt(0)
	v_mfma_scale_f32_16x16x128_f8f6f4 v[56:59], v[0:7], v[172:179], v[56:59], v160, v160 op_sel_hi:[0,0,0]
	v_mfma_scale_f32_16x16x128_f8f6f4 v[44:47], v[0:7], v[180:187], v[44:47], v160, v160 op_sel_hi:[0,0,0]
	v_mfma_scale_f32_16x16x128_f8f6f4 v[28:31], v[0:7], v[188:195], v[208:211], v160, v160 op_sel_hi:[0,0,0]
	v_mfma_scale_f32_16x16x128_f8f6f4 v[12:15], v[0:7], v[196:203], v[228:231], v160, v160 op_sel_hi:[0,0,0]
	v_mfma_scale_f32_16x16x128_f8f6f4 v[4:7], v[134:141], v[196:203], v[232:235], v160, v160 op_sel_hi:[0,0,0]
	v_mfma_scale_f32_16x16x128_f8f6f4 v[20:23], v[134:141], v[188:195], v[224:227], v160, v160 op_sel_hi:[0,0,0]
	v_mfma_scale_f32_16x16x128_f8f6f4 v[36:39], v[134:141], v[180:187], v[204:207], v160, v160 op_sel_hi:[0,0,0]
	v_mfma_scale_f32_16x16x128_f8f6f4 v[48:51], v[134:141], v[172:179], v[48:51], v160, v160 op_sel_hi:[0,0,0]
	s_setprio 0
	s_setprio 1
	s_waitcnt lgkmcnt(0)
	v_mfma_scale_f32_16x16x128_f8f6f4 v[60:63], v[142:149], v[172:179], v[60:63], v160, v160 op_sel_hi:[0,0,0]
	v_mfma_scale_f32_16x16x128_f8f6f4 v[40:43], v[142:149], v[180:187], v[40:43], v160, v160 op_sel_hi:[0,0,0]
	v_mfma_scale_f32_16x16x128_f8f6f4 v[24:27], v[142:149], v[188:195], v[240:243], v160, v160 op_sel_hi:[0,0,0]
	v_mfma_scale_f32_16x16x128_f8f6f4 v[8:11], v[142:149], v[196:203], v[248:251], v160, v160 op_sel_hi:[0,0,0]
	v_mfma_scale_f32_16x16x128_f8f6f4 v[0:3], v[164:171], v[196:203], v[128:131], v160, v160 op_sel_hi:[0,0,0]
	v_mfma_scale_f32_16x16x128_f8f6f4 v[16:19], v[164:171], v[188:195], v[244:247], v160, v160 op_sel_hi:[0,0,0]
	v_mfma_scale_f32_16x16x128_f8f6f4 v[32:35], v[164:171], v[180:187], v[236:239], v160, v160 op_sel_hi:[0,0,0]
	v_mfma_scale_f32_16x16x128_f8f6f4 v[52:55], v[164:171], v[172:179], v[52:55], v160, v160 op_sel_hi:[0,0,0]
	s_setprio 0
	s_barrier
	s_nop 11
	s_add_i32 s96, s96, 2
	s_add_u32 s92, s92, 0x10000
	s_addc_u32 s93, s93, 0
	s_cmp_gt_u32 s96, 29
	s_mov_b64 s[56:57], s[2:3]
	s_cbranch_scc0 .LBB0_1768
	s_and_b64 vcc, exec, s[14:15]
	s_cbranch_vccz .LBB0_1771
	s_barrier

.LBB0_1955:
	v_add_u32_e32 v142, 0x10000, v128
	v_add_u32_e32 v158, 0x14000, v128
	ds_read_b128 v[130:133], v142
	ds_read_b128 v[134:137], v142 offset:1024
	ds_read_b128 v[138:141], v142 offset:2048
	ds_read_b128 v[142:145], v142 offset:3072
	ds_read_b128 v[146:149], v158
	ds_read_b128 v[150:153], v158 offset:1024
	ds_read_b128 v[154:157], v158 offset:2048
	ds_read_b128 v[158:161], v158 offset:3072
	s_add_u32 s2, s26, 0x10000
	s_addc_u32 s3, s27, 0
	s_cmpk_eq_i32 s23, 0x4c
	s_cselect_b32 s28, s4, s2
	s_cselect_b32 s29, s5, s3
	s_cselect_b32 s40, s20, s19
	s_cselect_b32 s41, s21, s17
	s_add_u32 s38, s28, 0x8000
	s_addc_u32 s39, s29, 0
	ds_read_b128 v[162:165], v129
	ds_read_b128 v[166:169], v129 offset:1024
	ds_read_b128 v[170:173], v129 offset:2048
	ds_read_b128 v[174:177], v129 offset:3072
	ds_read_b128 v[178:181], v129 offset:4096
	ds_read_b128 v[182:185], v129 offset:5120
	ds_read_b128 v[192:195], v129 offset:6144
	ds_read_b128 v[196:199], v129 offset:7168
	s_add_u32 s42, s26, 0xc000
	s_addc_u32 s43, s27, 0
	s_mov_b32 m0, s63
	s_nop 0
	global_load_lds_dwordx4 v210, s[42:43]
	s_add_u32 s26, s26, 0xe000
	s_addc_u32 s27, s27, 0
	s_mov_b32 m0, s66
	s_nop 0
	global_load_lds_dwordx4 v210, s[26:27]
	s_waitcnt vmcnt(8)
	s_waitcnt lgkmcnt(0)
	s_barrier
	s_setprio 1
	s_waitcnt lgkmcnt(6)
	s_waitcnt lgkmcnt(0)
	v_mfma_scale_f32_16x16x128_f8f6f4 v[124:127], v[130:137], v[162:169], v[124:127], v212, v211 op_sel_hi:[0,0,0]
	v_mfma_scale_f32_16x16x128_f8f6f4 v[108:111], v[130:137], v[170:177], v[108:111], v212, v211 op_sel_hi:[0,0,0]
	v_mfma_scale_f32_16x16x128_f8f6f4 v[200:203], v[130:137], v[178:185], v[92:95], v212, v211 op_sel_hi:[0,0,0]
	v_mfma_scale_f32_16x16x128_f8f6f4 v[214:217], v[130:137], v[192:199], v[76:79], v212, v211 op_sel_hi:[0,0,0]
	v_mfma_scale_f32_16x16x128_f8f6f4 v[218:221], v[138:145], v[192:199], v[72:75], v212, v211 op_sel_hi:[0,0,0]
	v_mfma_scale_f32_16x16x128_f8f6f4 v[204:207], v[138:145], v[178:185], v[88:91], v212, v211 op_sel_hi:[0,0,0]
	v_mfma_scale_f32_16x16x128_f8f6f4 v[104:107], v[138:145], v[170:177], v[104:107], v212, v211 op_sel_hi:[0,0,0]
	v_mfma_scale_f32_16x16x128_f8f6f4 v[120:123], v[138:145], v[162:169], v[120:123], v212, v211 op_sel_hi:[0,0,0]
	s_setprio 0
	s_setprio 1
	v_mfma_scale_f32_16x16x128_f8f6f4 v[116:119], v[146:153], v[162:169], v[116:119], v212, v211 op_sel_hi:[0,0,0]
	v_mfma_scale_f32_16x16x128_f8f6f4 v[112:115], v[154:161], v[162:169], v[112:115], v212, v211 op_sel_hi:[0,0,0]
	v_mfma_scale_f32_16x16x128_f8f6f4 v[100:103], v[146:153], v[170:177], v[100:103], v212, v211 op_sel_hi:[0,0,0]
	v_mfma_scale_f32_16x16x128_f8f6f4 v[96:99], v[154:161], v[170:177], v[96:99], v212, v211 op_sel_hi:[0,0,0]
	v_mfma_scale_f32_16x16x128_f8f6f4 v[162:165], v[146:153], v[178:185], v[84:87], v212, v211 op_sel_hi:[0,0,0]
	v_mfma_scale_f32_16x16x128_f8f6f4 v[166:169], v[154:161], v[178:185], v[80:83], v212, v211 op_sel_hi:[0,0,0]
	v_mfma_scale_f32_16x16x128_f8f6f4 v[170:173], v[146:153], v[192:199], v[68:71], v212, v211 op_sel_hi:[0,0,0]
	v_mfma_scale_f32_16x16x128_f8f6f4 v[174:177], v[154:161], v[192:199], v[64:67], v212, v211 op_sel_hi:[0,0,0]
	s_setprio 0
	s_barrier
	s_nop 11
	s_add_u32 s26, s40, 0x2000
	s_nop 3
	ds_read_b128 v[64:67], v129 offset:16384
	ds_read_b128 v[68:71], v129 offset:17408
	ds_read_b128 v[72:75], v129 offset:18432
	ds_read_b128 v[76:79], v129 offset:19456
	ds_read_b128 v[80:83], v129 offset:20480
	ds_read_b128 v[84:87], v129 offset:21504
	ds_read_b128 v[88:91], v129 offset:22528
	ds_read_b128 v[92:95], v129 offset:23552
	s_mov_b32 m0, s46
	s_nop 0
	global_load_lds_dwordx4 v210, s[40:41]
	s_addc_u32 s27, s41, 0
	s_mov_b32 m0, s47
	s_nop 0
	global_load_lds_dwordx4 v210, s[26:27]
	s_add_u32 s26, s40, 0x4000
	s_addc_u32 s27, s41, 0
	s_mov_b32 m0, s48
	s_nop 0
	global_load_lds_dwordx4 v210, s[26:27]
	s_add_u32 s26, s40, 0x6000
	s_addc_u32 s27, s41, 0
	s_mov_b32 m0, s49
	s_nop 0
	global_load_lds_dwordx4 v210, s[26:27]
	s_add_u32 s26, s28, 0x2000
	s_mov_b32 m0, s45
	s_nop 0
	global_load_lds_dwordx4 v210, s[28:29]
	s_addc_u32 s27, s29, 0
	s_mov_b32 m0, s50
	s_nop 0
	global_load_lds_dwordx4 v210, s[26:27]
	s_waitcnt vmcnt(8)
	s_waitcnt lgkmcnt(0)
	s_barrier
	s_setprio 1
	s_waitcnt lgkmcnt(6)
	s_waitcnt lgkmcnt(0)
	v_mfma_scale_f32_16x16x128_f8f6f4 v[60:63], v[130:137], v[64:71], v[60:63], v212, v211 op_sel_hi:[0,0,0]
	v_mfma_scale_f32_16x16x128_f8f6f4 v[178:181], v[130:137], v[72:79], v[44:47], v212, v211 op_sel_hi:[0,0,0]
	v_mfma_scale_f32_16x16x128_f8f6f4 v[192:195], v[130:137], v[80:87], v[28:31], v212, v211 op_sel_hi:[0,0,0]
	v_mfma_scale_f32_16x16x128_f8f6f4 v[222:225], v[130:137], v[88:95], v[12:15], v212, v211 op_sel_hi:[0,0,0]
	v_mfma_scale_f32_16x16x128_f8f6f4 v[226:229], v[138:145], v[88:95], v[8:11], v212, v211 op_sel_hi:[0,0,0]
	v_mfma_scale_f32_16x16x128_f8f6f4 v[196:199], v[138:145], v[80:87], v[24:27], v212, v211 op_sel_hi:[0,0,0]
	v_mfma_scale_f32_16x16x128_f8f6f4 v[182:185], v[138:145], v[72:79], v[40:43], v212, v211 op_sel_hi:[0,0,0]
	v_mfma_scale_f32_16x16x128_f8f6f4 v[56:59], v[138:145], v[64:71], v[56:59], v212, v211 op_sel_hi:[0,0,0]
	s_setprio 0
	s_setprio 1
	s_waitcnt lgkmcnt(0)
	v_mfma_scale_f32_16x16x128_f8f6f4 v[52:55], v[146:153], v[64:71], v[52:55], v212, v211 op_sel_hi:[0,0,0]
	v_mfma_scale_f32_16x16x128_f8f6f4 v[230:233], v[146:153], v[72:79], v[36:39], v212, v211 op_sel_hi:[0,0,0]
	v_mfma_scale_f32_16x16x128_f8f6f4 v[238:241], v[146:153], v[80:87], v[20:23], v212, v211 op_sel_hi:[0,0,0]
	v_mfma_scale_f32_16x16x128_f8f6f4 v[246:249], v[146:153], v[88:95], v[4:7], v212, v211 op_sel_hi:[0,0,0]
	v_mfma_scale_f32_16x16x128_f8f6f4 v[186:189], v[154:161], v[88:95], v[0:3], v212, v211 op_sel_hi:[0,0,0]
	v_mfma_scale_f32_16x16x128_f8f6f4 v[242:245], v[154:161], v[80:87], v[16:19], v212, v211 op_sel_hi:[0,0,0]
	v_mfma_scale_f32_16x16x128_f8f6f4 v[234:237], v[154:161], v[72:79], v[32:35], v212, v211 op_sel_hi:[0,0,0]
	v_mfma_scale_f32_16x16x128_f8f6f4 v[48:51], v[154:161], v[64:71], v[48:51], v212, v211 op_sel_hi:[0,0,0]
	s_setprio 0
	s_barrier
	s_nop 11
	v_add_u32_e32 v8, 0x18000, v128
	s_nop 3
	ds_read_b128 v[0:3], v8
	ds_read_b128 v[4:7], v8 offset:1024
	ds_read_b128 v[16:19], v8 offset:2048
	ds_read_b128 v[20:23], v8 offset:3072
	v_add_u32_e32 v8, 0x1c000, v128
	ds_read_b128 v[130:133], v8
	ds_read_b128 v[134:137], v8 offset:1024
	ds_read_b128 v[138:141], v8 offset:2048
	ds_read_b128 v[142:145], v8 offset:3072
	ds_read_b128 v[8:11], v129 offset:32768
	ds_read_b128 v[12:15], v129 offset:33792
	ds_read_b128 v[24:27], v129 offset:34816
	ds_read_b128 v[28:31], v129 offset:35840
	ds_read_b128 v[32:35], v129 offset:36864
	ds_read_b128 v[36:39], v129 offset:37888
	ds_read_b128 v[40:43], v129 offset:38912
	ds_read_b128 v[44:47], v129 offset:39936
	s_add_u32 s26, s28, 0x4000
	s_addc_u32 s27, s29, 0
	s_mov_b32 m0, s51
	s_nop 0
	global_load_lds_dwordx4 v210, s[26:27]
	s_add_u32 s26, s28, 0x6000
	s_addc_u32 s27, s29, 0
	s_mov_b32 m0, s52
	s_nop 0
	global_load_lds_dwordx4 v210, s[26:27]
	s_waitcnt vmcnt(8)
	s_waitcnt lgkmcnt(0)
	s_barrier
	s_setprio 1
	s_waitcnt lgkmcnt(6)
	s_waitcnt lgkmcnt(0)
	v_mfma_scale_f32_16x16x128_f8f6f4 v[124:127], v[0:7], v[8:15], v[124:127], v212, v211 op_sel_hi:[0,0,0]
	v_mfma_scale_f32_16x16x128_f8f6f4 v[108:111], v[0:7], v[24:31], v[108:111], v212, v211 op_sel_hi:[0,0,0]
	v_mfma_scale_f32_16x16x128_f8f6f4 v[92:95], v[0:7], v[32:39], v[200:203], v212, v211 op_sel_hi:[0,0,0]
	v_mfma_scale_f32_16x16x128_f8f6f4 v[76:79], v[0:7], v[40:47], v[214:217], v212, v211 op_sel_hi:[0,0,0]
	v_mfma_scale_f32_16x16x128_f8f6f4 v[72:75], v[16:23], v[40:47], v[218:221], v212, v211 op_sel_hi:[0,0,0]
	v_mfma_scale_f32_16x16x128_f8f6f4 v[88:91], v[16:23], v[32:39], v[204:207], v212, v211 op_sel_hi:[0,0,0]
	v_mfma_scale_f32_16x16x128_f8f6f4 v[104:107], v[16:23], v[24:31], v[104:107], v212, v211 op_sel_hi:[0,0,0]
	v_mfma_scale_f32_16x16x128_f8f6f4 v[120:123], v[16:23], v[8:15], v[120:123], v212, v211 op_sel_hi:[0,0,0]
	s_setprio 0
	s_setprio 1
	s_waitcnt lgkmcnt(0)
	v_mfma_scale_f32_16x16x128_f8f6f4 v[116:119], v[130:137], v[8:15], v[116:119], v212, v211 op_sel_hi:[0,0,0]
	v_mfma_scale_f32_16x16x128_f8f6f4 v[100:103], v[130:137], v[24:31], v[100:103], v212, v211 op_sel_hi:[0,0,0]
	v_mfma_scale_f32_16x16x128_f8f6f4 v[84:87], v[130:137], v[32:39], v[162:165], v212, v211 op_sel_hi:[0,0,0]
	v_mfma_scale_f32_16x16x128_f8f6f4 v[68:71], v[130:137], v[40:47], v[170:173], v212, v211 op_sel_hi:[0,0,0]
	v_mfma_scale_f32_16x16x128_f8f6f4 v[64:67], v[138:145], v[40:47], v[174:177], v212, v211 op_sel_hi:[0,0,0]
	v_mfma_scale_f32_16x16x128_f8f6f4 v[80:83], v[138:145], v[32:39], v[166:169], v212, v211 op_sel_hi:[0,0,0]
	v_mfma_scale_f32_16x16x128_f8f6f4 v[96:99], v[138:145], v[24:31], v[96:99], v212, v211 op_sel_hi:[0,0,0]
	v_mfma_scale_f32_16x16x128_f8f6f4 v[112:115], v[138:145], v[8:15], v[112:115], v212, v211 op_sel_hi:[0,0,0]
	s_setprio 0
	s_barrier
	s_nop 11
	s_add_u32 s26, s40, 0x8000
	s_addc_u32 s27, s41, 0
	ds_read_b128 v[32:35], v129 offset:49152
	ds_read_b128 v[36:39], v129 offset:50176
	ds_read_b128 v[146:149], v129 offset:51200
	ds_read_b128 v[150:153], v129 offset:52224
	ds_read_b128 v[154:157], v129 offset:53248
	ds_read_b128 v[158:161], v129 offset:54272
	ds_read_b128 v[162:165], v129 offset:55296
	ds_read_b128 v[166:169], v129 offset:56320
	s_mov_b32 m0, s53
	s_nop 0
	global_load_lds_dwordx4 v210, s[26:27]
	s_add_u32 s26, s40, 0xa000
	s_addc_u32 s27, s41, 0
	s_mov_b32 m0, s54
	s_nop 0
	global_load_lds_dwordx4 v210, s[26:27]
	s_add_u32 s26, s40, 0xc000
	s_addc_u32 s27, s41, 0
	s_mov_b32 m0, s57
	s_nop 0
	global_load_lds_dwordx4 v210, s[26:27]
	s_add_u32 s26, s40, 0xe000
	s_addc_u32 s27, s41, 0
	s_mov_b32 m0, s58
	s_nop 0
	global_load_lds_dwordx4 v210, s[26:27]
	s_add_u32 s26, s28, 0xa000
	s_mov_b32 m0, s55
	s_nop 0
	global_load_lds_dwordx4 v210, s[38:39]
	s_addc_u32 s27, s29, 0
	s_mov_b32 m0, s56
	s_nop 0
	global_load_lds_dwordx4 v210, s[26:27]
	s_waitcnt vmcnt(8)
	s_waitcnt lgkmcnt(0)
	s_barrier
	s_setprio 1
	s_waitcnt lgkmcnt(6)
	s_waitcnt lgkmcnt(0)
	v_mfma_scale_f32_16x16x128_f8f6f4 v[60:63], v[0:7], v[32:39], v[60:63], v212, v211 op_sel_hi:[0,0,0]
	v_mfma_scale_f32_16x16x128_f8f6f4 v[44:47], v[0:7], v[146:153], v[178:181], v212, v211 op_sel_hi:[0,0,0]
	v_mfma_scale_f32_16x16x128_f8f6f4 v[28:31], v[0:7], v[154:161], v[192:195], v212, v211 op_sel_hi:[0,0,0]
	v_mfma_scale_f32_16x16x128_f8f6f4 v[12:15], v[0:7], v[162:169], v[222:225], v212, v211 op_sel_hi:[0,0,0]
	v_mfma_scale_f32_16x16x128_f8f6f4 v[8:11], v[16:23], v[162:169], v[226:229], v212, v211 op_sel_hi:[0,0,0]
	v_mfma_scale_f32_16x16x128_f8f6f4 v[24:27], v[16:23], v[154:161], v[196:199], v212, v211 op_sel_hi:[0,0,0]
	v_mfma_scale_f32_16x16x128_f8f6f4 v[40:43], v[16:23], v[146:153], v[182:185], v212, v211 op_sel_hi:[0,0,0]
	v_mfma_scale_f32_16x16x128_f8f6f4 v[56:59], v[16:23], v[32:39], v[56:59], v212, v211 op_sel_hi:[0,0,0]
	s_setprio 0
	s_setprio 1
	v_mfma_scale_f32_16x16x128_f8f6f4 v[52:55], v[130:137], v[32:39], v[52:55], v212, v211 op_sel_hi:[0,0,0]
	v_mfma_scale_f32_16x16x128_f8f6f4 v[48:51], v[138:145], v[32:39], v[48:51], v212, v211 op_sel_hi:[0,0,0]
	v_mfma_scale_f32_16x16x128_f8f6f4 v[36:39], v[130:137], v[146:153], v[230:233], v212, v211 op_sel_hi:[0,0,0]
	v_mfma_scale_f32_16x16x128_f8f6f4 v[32:35], v[138:145], v[146:153], v[234:237], v212, v211 op_sel_hi:[0,0,0]
	v_mfma_scale_f32_16x16x128_f8f6f4 v[20:23], v[130:137], v[154:161], v[238:241], v212, v211 op_sel_hi:[0,0,0]
	v_mfma_scale_f32_16x16x128_f8f6f4 v[16:19], v[138:145], v[154:161], v[242:245], v212, v211 op_sel_hi:[0,0,0]
	v_mfma_scale_f32_16x16x128_f8f6f4 v[4:7], v[130:137], v[162:169], v[246:249], v212, v211 op_sel_hi:[0,0,0]
	v_mfma_scale_f32_16x16x128_f8f6f4 v[0:3], v[138:145], v[162:169], v[186:189], v212, v211 op_sel_hi:[0,0,0]
	s_setprio 0
	s_barrier
	s_nop 11
	s_add_i32 s23, s23, 2
	s_add_u32 s19, s19, 0x10000
	s_addc_u32 s17, s17, 0
	s_cmpk_gt_u32 s23, 0x4d
	s_mov_b64 s[26:27], s[2:3]
	s_cbranch_scc0 .LBB0_1955
	s_and_b64 vcc, exec, s[12:13]
	s_cbranch_vccz .LBB0_1958
	s_barrier
